# GEMM accumulator clears between tiles use v_mov_b64 (64 instead of 128 moves per tile per wave)
# speedup vs baseline: 1.0187x; 1.0042x over previous
;     __device__ bool next(int i, Unit& u) const { return map((long)i * G + c, u); }
;     __device__ bool next(int i, Unit& u) const { const int t = i / 3, b = i - 3 * t; if (!so.map((long)t * so.G + so.c, u)) return false; u.pn += 8 * b; return true; }
; template <class Epi, class Sched, bool AREMAP>
; __device__ __forceinline__ void gemm_phase(LAS unsigned char* lds, const Gemm g, const Sched& S, const Epi& E, int wv) {
;     ...
;         const bool has_next = S.next(ui + 1, nxt);
;         const char* nA = has_next ? PG8_UA(nxt) : cA; const char* nB = has_next ? PG8_UB(nxt) : cB;
;     ...
; #pragma unroll
;         for (int a = 0; a < 2; ++a)
; #pragma unroll
;             for (int b = 0; b < 2; ++b)
; #pragma unroll
;                 for (int m = 0; m < 4; ++m)
; #pragma unroll
;                     for (int n = 0; n < 2; ++n) acc[a][b][m][n] = (f32x4){0.f, 0.f, 0.f, 0.f};
.LBB0_201:
	v_mov_b64_e32 v[2:3], 0x1000
	s_ashr_i32 s11, s10, 31
	v_cmp_lt_i64_e32 vcc, s[12:13], v[2:3]
	s_lshl_b64 s[12:13], s[10:11], 20
	s_add_u32 s12, s27, s12
	s_addc_u32 s13, s28, s13
	s_and_b64 s[14:15], vcc, exec
	s_cselect_b32 s11, s13, s19
	s_cselect_b32 s47, s12, s18
	s_ashr_i32 s9, s8, 31
	s_lshl_b64 s[14:15], s[8:9], 20
	s_add_u32 s14, s2, s14
	s_addc_u32 s15, s3, s15
	s_and_b64 s[20:21], vcc, exec
	s_cselect_b32 s9, s15, s17
	s_cselect_b32 s52, s14, s16
	s_add_u32 s53, s16, 0x100
	s_addc_u32 s55, s17, 0
	s_add_u32 s16, s18, 0x80080
	v_mov_b64_e32 v[2:3], 0
	s_addc_u32 s17, s19, 0
	s_mov_b32 s56, -2
	v_mov_b64_e32 v[4:5], v[2:3]
	v_mov_b64_e32 v[6:7], v[2:3]
	v_mov_b64_e32 v[8:9], v[2:3]
	v_mov_b64_e32 v[10:11], v[2:3]
	v_mov_b64_e32 v[12:13], v[2:3]
	v_mov_b64_e32 v[14:15], v[2:3]
	v_mov_b64_e32 v[16:17], v[2:3]
	v_mov_b64_e32 v[26:27], v[2:3]
	v_mov_b64_e32 v[28:29], v[2:3]
	v_mov_b64_e32 v[30:31], v[2:3]
	v_mov_b64_e32 v[32:33], v[2:3]
	v_mov_b64_e32 v[42:43], v[2:3]
	v_mov_b64_e32 v[44:45], v[2:3]
	v_mov_b64_e32 v[46:47], v[2:3]
	v_mov_b64_e32 v[48:49], v[2:3]
	v_mov_b64_e32 v[18:19], v[2:3]
	v_mov_b64_e32 v[20:21], v[2:3]
	v_mov_b64_e32 v[22:23], v[2:3]
	v_mov_b64_e32 v[24:25], v[2:3]
	v_mov_b64_e32 v[34:35], v[2:3]
	v_mov_b64_e32 v[36:37], v[2:3]
	v_mov_b64_e32 v[38:39], v[2:3]
	v_mov_b64_e32 v[40:41], v[2:3]
	v_mov_b64_e32 v[50:51], v[2:3]
	v_mov_b64_e32 v[52:53], v[2:3]
	v_mov_b64_e32 v[54:55], v[2:3]
	v_mov_b64_e32 v[56:57], v[2:3]
	v_mov_b64_e32 v[58:59], v[2:3]
	v_mov_b64_e32 v[60:61], v[2:3]
	v_mov_b64_e32 v[62:63], v[2:3]
	v_mov_b64_e32 v[64:65], v[2:3]
	v_mov_b64_e32 v[66:67], v[2:3]
	v_mov_b64_e32 v[68:69], v[2:3]
	v_mov_b64_e32 v[70:71], v[2:3]
	v_mov_b64_e32 v[72:73], v[2:3]
	v_mov_b64_e32 v[74:75], v[2:3]
	v_mov_b64_e32 v[76:77], v[2:3]
	v_mov_b64_e32 v[78:79], v[2:3]
	v_mov_b64_e32 v[80:81], v[2:3]
	v_mov_b64_e32 v[90:91], v[2:3]
	v_mov_b64_e32 v[92:93], v[2:3]
	v_mov_b64_e32 v[94:95], v[2:3]
	v_mov_b64_e32 v[96:97], v[2:3]
	v_mov_b64_e32 v[106:107], v[2:3]
	v_mov_b64_e32 v[108:109], v[2:3]
	v_mov_b64_e32 v[110:111], v[2:3]
	v_mov_b64_e32 v[112:113], v[2:3]
	v_mov_b64_e32 v[82:83], v[2:3]
	v_mov_b64_e32 v[84:85], v[2:3]
	v_mov_b64_e32 v[86:87], v[2:3]
	v_mov_b64_e32 v[88:89], v[2:3]
	v_mov_b64_e32 v[98:99], v[2:3]
	v_mov_b64_e32 v[100:101], v[2:3]
	v_mov_b64_e32 v[102:103], v[2:3]
	v_mov_b64_e32 v[104:105], v[2:3]
	v_mov_b64_e32 v[114:115], v[2:3]
	v_mov_b64_e32 v[116:117], v[2:3]
	v_mov_b64_e32 v[118:119], v[2:3]
	v_mov_b64_e32 v[120:121], v[2:3]
	v_mov_b64_e32 v[122:123], v[2:3]
	v_mov_b64_e32 v[124:125], v[2:3]
	v_mov_b64_e32 v[126:127], v[2:3]
	v_mov_b64_e32 v[128:129], v[2:3]

; template <class Epi, class Sched, bool AREMAP>
; __device__ __forceinline__ void gemm_phase(LAS unsigned char* lds, const Gemm g, const Sched& S, const Epi& E, int wv) {
;     ...
;         const char* nA = has_next ? PG8_UA(nxt) : cA; const char* nB = has_next ? PG8_UB(nxt) : cB;
;         for (int t = 0; t < nt; t += 2) {
;             const bool last = (t == nt - 2);
;             const char* a1 = cA + (size_t)(t + 1) * kstep;
;             const char* a2 = last ? nA : cA + (size_t)(t + 2) * kstep; const char* b2 = last ? nB : cB + (size_t)(t + 2) * kstep;
;     ...
; #pragma unroll
;         for (int a = 0; a < 2; ++a)
; #pragma unroll
;             for (int b = 0; b < 2; ++b)
; #pragma unroll
;                 for (int m = 0; m < 4; ++m)
; #pragma unroll
;                     for (int n = 0; n < 2; ++n) acc[a][b][m][n] = (f32x4){0.f, 0.f, 0.f, 0.f};
.LBB0_396:
	s_ashr_i32 s7, s6, 31
	s_lshl_b64 s[12:13], s[6:7], 19
	s_add_u32 s12, s23, s12
	s_addc_u32 s13, s25, s13
	s_and_b64 s[2:3], s[2:3], exec
	s_cselect_b32 s7, s13, s15
	s_cselect_b32 s9, s12, s14
	s_add_u32 s47, s14, 0x100
	s_addc_u32 s52, s15, 0
	s_add_u32 s2, s16, 0x40080
	v_mov_b64_e32 v[2:3], 0
	s_addc_u32 s3, s17, 0
	s_mov_b32 s53, -2
	v_mov_b64_e32 v[4:5], v[2:3]
	v_mov_b64_e32 v[6:7], v[2:3]
	v_mov_b64_e32 v[8:9], v[2:3]
	v_mov_b64_e32 v[10:11], v[2:3]
	v_mov_b64_e32 v[12:13], v[2:3]
	v_mov_b64_e32 v[14:15], v[2:3]
	v_mov_b64_e32 v[16:17], v[2:3]
	v_mov_b64_e32 v[26:27], v[2:3]
	v_mov_b64_e32 v[28:29], v[2:3]
	v_mov_b64_e32 v[30:31], v[2:3]
	v_mov_b64_e32 v[32:33], v[2:3]
	v_mov_b64_e32 v[42:43], v[2:3]
	v_mov_b64_e32 v[44:45], v[2:3]
	v_mov_b64_e32 v[46:47], v[2:3]
	v_mov_b64_e32 v[48:49], v[2:3]
	v_mov_b64_e32 v[18:19], v[2:3]
	v_mov_b64_e32 v[20:21], v[2:3]
	v_mov_b64_e32 v[22:23], v[2:3]
	v_mov_b64_e32 v[24:25], v[2:3]
	v_mov_b64_e32 v[34:35], v[2:3]
	v_mov_b64_e32 v[36:37], v[2:3]
	v_mov_b64_e32 v[38:39], v[2:3]
	v_mov_b64_e32 v[40:41], v[2:3]
	v_mov_b64_e32 v[50:51], v[2:3]
	v_mov_b64_e32 v[52:53], v[2:3]
	v_mov_b64_e32 v[54:55], v[2:3]
	v_mov_b64_e32 v[56:57], v[2:3]
	v_mov_b64_e32 v[58:59], v[2:3]
	v_mov_b64_e32 v[60:61], v[2:3]
	v_mov_b64_e32 v[62:63], v[2:3]
	v_mov_b64_e32 v[64:65], v[2:3]
	v_mov_b64_e32 v[66:67], v[2:3]
	v_mov_b64_e32 v[68:69], v[2:3]
	v_mov_b64_e32 v[70:71], v[2:3]
	v_mov_b64_e32 v[72:73], v[2:3]
	v_mov_b64_e32 v[74:75], v[2:3]
	v_mov_b64_e32 v[76:77], v[2:3]
	v_mov_b64_e32 v[78:79], v[2:3]
	v_mov_b64_e32 v[80:81], v[2:3]
	v_mov_b64_e32 v[90:91], v[2:3]
	v_mov_b64_e32 v[92:93], v[2:3]
	v_mov_b64_e32 v[94:95], v[2:3]
	v_mov_b64_e32 v[96:97], v[2:3]
	v_mov_b64_e32 v[106:107], v[2:3]
	v_mov_b64_e32 v[108:109], v[2:3]
	v_mov_b64_e32 v[110:111], v[2:3]
	v_mov_b64_e32 v[112:113], v[2:3]
	v_mov_b64_e32 v[82:83], v[2:3]
	v_mov_b64_e32 v[84:85], v[2:3]
	v_mov_b64_e32 v[86:87], v[2:3]
	v_mov_b64_e32 v[88:89], v[2:3]
	v_mov_b64_e32 v[98:99], v[2:3]
	v_mov_b64_e32 v[100:101], v[2:3]
	v_mov_b64_e32 v[102:103], v[2:3]
	v_mov_b64_e32 v[104:105], v[2:3]
	v_mov_b64_e32 v[114:115], v[2:3]
	v_mov_b64_e32 v[116:117], v[2:3]
	v_mov_b64_e32 v[118:119], v[2:3]
	v_mov_b64_e32 v[120:121], v[2:3]
	v_mov_b64_e32 v[122:123], v[2:3]
	v_mov_b64_e32 v[124:125], v[2:3]
	v_mov_b64_e32 v[126:127], v[2:3]
	v_mov_b64_e32 v[128:129], v[2:3]

; template <class Epi, class Sched, bool AREMAP>
; __device__ __forceinline__ void gemm_phase(LAS unsigned char* lds, const Gemm g, const Sched& S, const Epi& E, int wv) {
;     ...
;         const char* nA = has_next ? PG8_UA(nxt) : cA; const char* nB = has_next ? PG8_UB(nxt) : cB;
;         for (int t = 0; t < nt; t += 2) {
;             const bool last = (t == nt - 2);
;             const char* a1 = cA + (size_t)(t + 1) * kstep;
;             const char* a2 = last ? nA : cA + (size_t)(t + 2) * kstep; const char* b2 = last ? nB : cB + (size_t)(t + 2) * kstep;
;     ...
; #pragma unroll
;         for (int a = 0; a < 2; ++a)
; #pragma unroll
;             for (int b = 0; b < 2; ++b)
; #pragma unroll
;                 for (int m = 0; m < 4; ++m)
; #pragma unroll
;                     for (int n = 0; n < 2; ++n) acc[a][b][m][n] = (f32x4){0.f, 0.f, 0.f, 0.f};
.LBB0_425:
	s_ashr_i32 s11, s10, 31
	v_cmp_lt_i64_e32 vcc, s[14:15], v[190:191]
	s_lshl_b64 s[14:15], s[10:11], 20
	s_add_u32 s14, s28, s14
	s_addc_u32 s15, s29, s15
	s_and_b64 s[16:17], vcc, exec
	s_cselect_b32 s3, s15, s21
	s_cselect_b32 s5, s14, s20
	s_ashr_i32 s13, s12, 31
	s_lshl_b64 s[16:17], s[12:13], 20
	s_add_u32 s16, s30, s16
	s_addc_u32 s17, s31, s17
	s_and_b64 s[22:23], vcc, exec
	s_cselect_b32 s11, s17, s19
	s_cselect_b32 s13, s16, s18
	s_add_u32 s36, s18, 0x100
	s_addc_u32 s37, s19, 0
	s_add_u32 s18, s20, 0x80080
	v_mov_b64_e32 v[2:3], 0
	s_addc_u32 s19, s21, 0
	s_mov_b32 s46, -2
	v_mov_b64_e32 v[4:5], v[2:3]
	v_mov_b64_e32 v[6:7], v[2:3]
	v_mov_b64_e32 v[8:9], v[2:3]
	v_mov_b64_e32 v[18:19], v[2:3]
	v_mov_b64_e32 v[20:21], v[2:3]
	v_mov_b64_e32 v[22:23], v[2:3]
	v_mov_b64_e32 v[24:25], v[2:3]
	v_mov_b64_e32 v[34:35], v[2:3]
	v_mov_b64_e32 v[36:37], v[2:3]
	v_mov_b64_e32 v[38:39], v[2:3]
	v_mov_b64_e32 v[40:41], v[2:3]
	v_mov_b64_e32 v[50:51], v[2:3]
	v_mov_b64_e32 v[52:53], v[2:3]
	v_mov_b64_e32 v[54:55], v[2:3]
	v_mov_b64_e32 v[56:57], v[2:3]
	v_mov_b64_e32 v[10:11], v[2:3]
	v_mov_b64_e32 v[12:13], v[2:3]
	v_mov_b64_e32 v[14:15], v[2:3]
	v_mov_b64_e32 v[16:17], v[2:3]
	v_mov_b64_e32 v[26:27], v[2:3]
	v_mov_b64_e32 v[28:29], v[2:3]
	v_mov_b64_e32 v[30:31], v[2:3]
	v_mov_b64_e32 v[32:33], v[2:3]
	v_mov_b64_e32 v[42:43], v[2:3]
	v_mov_b64_e32 v[44:45], v[2:3]
	v_mov_b64_e32 v[46:47], v[2:3]
	v_mov_b64_e32 v[48:49], v[2:3]
	v_mov_b64_e32 v[58:59], v[2:3]
	v_mov_b64_e32 v[60:61], v[2:3]
	v_mov_b64_e32 v[62:63], v[2:3]
	v_mov_b64_e32 v[64:65], v[2:3]
	v_mov_b64_e32 v[66:67], v[2:3]
	v_mov_b64_e32 v[68:69], v[2:3]
	v_mov_b64_e32 v[70:71], v[2:3]
	v_mov_b64_e32 v[72:73], v[2:3]
	v_mov_b64_e32 v[82:83], v[2:3]
	v_mov_b64_e32 v[84:85], v[2:3]
	v_mov_b64_e32 v[86:87], v[2:3]
	v_mov_b64_e32 v[88:89], v[2:3]
	v_mov_b64_e32 v[98:99], v[2:3]
	v_mov_b64_e32 v[100:101], v[2:3]
	v_mov_b64_e32 v[102:103], v[2:3]
	v_mov_b64_e32 v[104:105], v[2:3]
	v_mov_b64_e32 v[114:115], v[2:3]
	v_mov_b64_e32 v[116:117], v[2:3]
	v_mov_b64_e32 v[118:119], v[2:3]
	v_mov_b64_e32 v[120:121], v[2:3]
	v_mov_b64_e32 v[74:75], v[2:3]
	v_mov_b64_e32 v[76:77], v[2:3]
	v_mov_b64_e32 v[78:79], v[2:3]
	v_mov_b64_e32 v[80:81], v[2:3]
	v_mov_b64_e32 v[90:91], v[2:3]
	v_mov_b64_e32 v[92:93], v[2:3]
	v_mov_b64_e32 v[94:95], v[2:3]
	v_mov_b64_e32 v[96:97], v[2:3]
	v_mov_b64_e32 v[106:107], v[2:3]
	v_mov_b64_e32 v[108:109], v[2:3]
	v_mov_b64_e32 v[110:111], v[2:3]
	v_mov_b64_e32 v[112:113], v[2:3]
	v_mov_b64_e32 v[122:123], v[2:3]
	v_mov_b64_e32 v[124:125], v[2:3]
	v_mov_b64_e32 v[126:127], v[2:3]
	v_mov_b64_e32 v[128:129], v[2:3]

; template <class Epi, class Sched, bool AREMAP>
; __device__ __forceinline__ void gemm_phase(LAS unsigned char* lds, const Gemm g, const Sched& S, const Epi& E, int wv) {
;     ...
;         const char* nA = has_next ? PG8_UA(nxt) : cA; const char* nB = has_next ? PG8_UB(nxt) : cB;
;         for (int t = 0; t < nt; t += 2) {
;             const bool last = (t == nt - 2);
;             const char* a1 = cA + (size_t)(t + 1) * kstep;
;             const char* a2 = last ? nA : cA + (size_t)(t + 2) * kstep; const char* b2 = last ? nB : cB + (size_t)(t + 2) * kstep;
;     ...
; #pragma unroll
;         for (int a = 0; a < 2; ++a)
; #pragma unroll
;             for (int b = 0; b < 2; ++b)
; #pragma unroll
;                 for (int m = 0; m < 4; ++m)
; #pragma unroll
;                     for (int n = 0; n < 2; ++n) acc[a][b][m][n] = (f32x4){0.f, 0.f, 0.f, 0.f};
.LBB0_551:
	s_ashr_i32 s23, s22, 31
	v_cmp_lt_i64_e32 vcc, s[24:25], v[190:191]
	s_lshl_b64 s[24:25], s[22:23], 20
	s_add_u32 s24, s41, s24
	s_addc_u32 s25, s46, s25
	s_and_b64 s[26:27], vcc, exec
	s_cselect_b32 s23, s25, s3
	s_cselect_b32 s72, s24, s2
	s_ashr_i32 s21, s20, 31
	s_lshl_b64 s[26:27], s[20:21], 20
	s_add_u32 s26, s47, s26
	s_addc_u32 s27, s52, s27
	s_and_b64 s[62:63], vcc, exec
	s_cselect_b32 s21, s27, s35
	s_cselect_b32 s73, s26, s34
	s_add_u32 s74, s34, 0x100
	v_mov_b64_e32 v[2:3], 0
	s_addc_u32 s75, s35, 0
	s_mov_b32 s76, -2
	v_mov_b64_e32 v[4:5], v[2:3]
	v_mov_b64_e32 v[18:19], v[2:3]
	v_mov_b64_e32 v[20:21], v[2:3]
	v_mov_b64_e32 v[6:7], v[2:3]
	v_mov_b64_e32 v[8:9], v[2:3]
	v_mov_b64_e32 v[22:23], v[2:3]
	v_mov_b64_e32 v[24:25], v[2:3]
	v_mov_b64_e32 v[10:11], v[2:3]
	v_mov_b64_e32 v[12:13], v[2:3]
	v_mov_b64_e32 v[26:27], v[2:3]
	v_mov_b64_e32 v[28:29], v[2:3]
	v_mov_b64_e32 v[14:15], v[2:3]
	v_mov_b64_e32 v[16:17], v[2:3]
	v_mov_b64_e32 v[30:31], v[2:3]
	v_mov_b64_e32 v[32:33], v[2:3]
	v_mov_b64_e32 v[34:35], v[2:3]
	v_mov_b64_e32 v[36:37], v[2:3]
	v_mov_b64_e32 v[50:51], v[2:3]
	v_mov_b64_e32 v[52:53], v[2:3]
	v_mov_b64_e32 v[38:39], v[2:3]
	v_mov_b64_e32 v[40:41], v[2:3]
	v_mov_b64_e32 v[54:55], v[2:3]
	v_mov_b64_e32 v[56:57], v[2:3]
	v_mov_b64_e32 v[42:43], v[2:3]
	v_mov_b64_e32 v[44:45], v[2:3]
	v_mov_b64_e32 v[58:59], v[2:3]
	v_mov_b64_e32 v[60:61], v[2:3]
	v_mov_b64_e32 v[46:47], v[2:3]
	v_mov_b64_e32 v[48:49], v[2:3]
	v_mov_b64_e32 v[62:63], v[2:3]
	v_mov_b64_e32 v[64:65], v[2:3]
	v_mov_b64_e32 v[66:67], v[2:3]
	v_mov_b64_e32 v[68:69], v[2:3]
	v_mov_b64_e32 v[82:83], v[2:3]
	v_mov_b64_e32 v[84:85], v[2:3]
	v_mov_b64_e32 v[70:71], v[2:3]
	v_mov_b64_e32 v[72:73], v[2:3]
	v_mov_b64_e32 v[86:87], v[2:3]
	v_mov_b64_e32 v[88:89], v[2:3]
	v_mov_b64_e32 v[74:75], v[2:3]
	v_mov_b64_e32 v[76:77], v[2:3]
	v_mov_b64_e32 v[90:91], v[2:3]
	v_mov_b64_e32 v[92:93], v[2:3]
	v_mov_b64_e32 v[78:79], v[2:3]
	v_mov_b64_e32 v[80:81], v[2:3]
	v_mov_b64_e32 v[94:95], v[2:3]
	v_mov_b64_e32 v[96:97], v[2:3]
	v_mov_b64_e32 v[98:99], v[2:3]
	v_mov_b64_e32 v[100:101], v[2:3]
	v_mov_b64_e32 v[114:115], v[2:3]
	v_mov_b64_e32 v[116:117], v[2:3]
	v_mov_b64_e32 v[102:103], v[2:3]
	v_mov_b64_e32 v[104:105], v[2:3]
	v_mov_b64_e32 v[118:119], v[2:3]
	v_mov_b64_e32 v[120:121], v[2:3]
	v_mov_b64_e32 v[106:107], v[2:3]
	v_mov_b64_e32 v[108:109], v[2:3]
	v_mov_b64_e32 v[122:123], v[2:3]
	v_mov_b64_e32 v[124:125], v[2:3]
	v_mov_b64_e32 v[110:111], v[2:3]
	v_mov_b64_e32 v[112:113], v[2:3]
	v_mov_b64_e32 v[126:127], v[2:3]
	v_mov_b64_e32 v[128:129], v[2:3]

; template <class Epi, class Sched, bool AREMAP>
; __device__ __forceinline__ void gemm_phase(LAS unsigned char* lds, const Gemm g, const Sched& S, const Epi& E, int wv) {
;     ...
;         const char* nA = has_next ? PG8_UA(nxt) : cA; const char* nB = has_next ? PG8_UB(nxt) : cB;
;         for (int t = 0; t < nt; t += 2) {
;             const bool last = (t == nt - 2);
;             const char* a1 = cA + (size_t)(t + 1) * kstep;
;             const char* a2 = last ? nA : cA + (size_t)(t + 2) * kstep; const char* b2 = last ? nB : cB + (size_t)(t + 2) * kstep;
;     ...
; #pragma unroll
;         for (int a = 0; a < 2; ++a)
; #pragma unroll
;             for (int b = 0; b < 2; ++b)
; #pragma unroll
;                 for (int m = 0; m < 4; ++m)
; #pragma unroll
;                     for (int n = 0; n < 2; ++n) acc[a][b][m][n] = (f32x4){0.f, 0.f, 0.f, 0.f};
.LBB0_618:
	s_ashr_i32 s67, s66, 31
	s_lshl_b64 s[46:47], s[66:67], 20
	v_mov_b64_e32 v[2:3], 0x1600
	s_add_u32 s68, s65, s46
	v_cmp_lt_i64_e32 vcc, s[56:57], v[2:3]
	s_addc_u32 s69, s72, s47
	s_and_b64 s[46:47], vcc, exec
	s_cselect_b32 s46, s69, s81
	s_cselect_b32 s47, s68, s80
	s_ashr_i32 s63, s62, 31
	s_lshl_b64 s[56:57], s[62:63], 20
	s_add_u32 s56, s73, s56
	s_addc_u32 s57, s74, s57
	s_and_b64 s[96:97], vcc, exec
	s_cselect_b32 s63, s57, s79
	s_cselect_b32 s67, s56, s78
	s_add_u32 s77, s78, 0x100
	s_addc_u32 vcc_lo, s79, 0
	s_add_u32 s78, s80, 0x40080
	v_mov_b64_e32 v[2:3], 0
	s_addc_u32 s79, s81, 0
	s_mov_b32 vcc_hi, -2
	v_mov_b64_e32 v[4:5], v[2:3]
	v_mov_b64_e32 v[66:67], v[2:3]
	v_mov_b64_e32 v[68:69], v[2:3]
	v_mov_b64_e32 v[10:11], v[2:3]
	v_mov_b64_e32 v[12:13], v[2:3]
	v_mov_b64_e32 v[74:75], v[2:3]
	v_mov_b64_e32 v[76:77], v[2:3]
	v_mov_b64_e32 v[18:19], v[2:3]
	v_mov_b64_e32 v[20:21], v[2:3]
	v_mov_b64_e32 v[82:83], v[2:3]
	v_mov_b64_e32 v[84:85], v[2:3]
	v_mov_b64_e32 v[26:27], v[2:3]
	v_mov_b64_e32 v[28:29], v[2:3]
	v_mov_b64_e32 v[90:91], v[2:3]
	v_mov_b64_e32 v[92:93], v[2:3]
	v_mov_b64_e32 v[6:7], v[2:3]
	v_mov_b64_e32 v[8:9], v[2:3]
	v_mov_b64_e32 v[70:71], v[2:3]
	v_mov_b64_e32 v[72:73], v[2:3]
	v_mov_b64_e32 v[14:15], v[2:3]
	v_mov_b64_e32 v[16:17], v[2:3]
	v_mov_b64_e32 v[78:79], v[2:3]
	v_mov_b64_e32 v[80:81], v[2:3]
	v_mov_b64_e32 v[22:23], v[2:3]
	v_mov_b64_e32 v[24:25], v[2:3]
	v_mov_b64_e32 v[86:87], v[2:3]
	v_mov_b64_e32 v[88:89], v[2:3]
	v_mov_b64_e32 v[30:31], v[2:3]
	v_mov_b64_e32 v[32:33], v[2:3]
	v_mov_b64_e32 v[94:95], v[2:3]
	v_mov_b64_e32 v[96:97], v[2:3]
	v_mov_b64_e32 v[34:35], v[2:3]
	v_mov_b64_e32 v[36:37], v[2:3]
	v_mov_b64_e32 v[98:99], v[2:3]
	v_mov_b64_e32 v[100:101], v[2:3]
	v_mov_b64_e32 v[42:43], v[2:3]
	v_mov_b64_e32 v[44:45], v[2:3]
	v_mov_b64_e32 v[106:107], v[2:3]
	v_mov_b64_e32 v[108:109], v[2:3]
	v_mov_b64_e32 v[50:51], v[2:3]
	v_mov_b64_e32 v[52:53], v[2:3]
	v_mov_b64_e32 v[114:115], v[2:3]
	v_mov_b64_e32 v[116:117], v[2:3]
	v_mov_b64_e32 v[58:59], v[2:3]
	v_mov_b64_e32 v[60:61], v[2:3]
	v_mov_b64_e32 v[122:123], v[2:3]
	v_mov_b64_e32 v[124:125], v[2:3]
	v_mov_b64_e32 v[38:39], v[2:3]
	v_mov_b64_e32 v[40:41], v[2:3]
	v_mov_b64_e32 v[102:103], v[2:3]
	v_mov_b64_e32 v[104:105], v[2:3]
	v_mov_b64_e32 v[46:47], v[2:3]
	v_mov_b64_e32 v[48:49], v[2:3]
	v_mov_b64_e32 v[110:111], v[2:3]
	v_mov_b64_e32 v[112:113], v[2:3]
	v_mov_b64_e32 v[54:55], v[2:3]
	v_mov_b64_e32 v[56:57], v[2:3]
	v_mov_b64_e32 v[118:119], v[2:3]
	v_mov_b64_e32 v[120:121], v[2:3]
	v_mov_b64_e32 v[62:63], v[2:3]
	v_mov_b64_e32 v[64:65], v[2:3]
	v_mov_b64_e32 v[126:127], v[2:3]
	v_mov_b64_e32 v[128:129], v[2:3]

; template <class Epi, class Sched, bool AREMAP>
; __device__ __forceinline__ void gemm_phase(LAS unsigned char* lds, const Gemm g, const Sched& S, const Epi& E, int wv) {
;     ...
;             const char* a2 = last ? nA : cA + (size_t)(t + 2) * kstep; const char* b2 = last ? nB : cB + (size_t)(t + 2) * kstep;
;     ...
; #pragma unroll
;         for (int a = 0; a < 2; ++a)
; #pragma unroll
;             for (int b = 0; b < 2; ++b)
; #pragma unroll
;                 for (int m = 0; m < 4; ++m)
; #pragma unroll
;                     for (int n = 0; n < 2; ++n) acc[a][b][m][n] = (f32x4){0.f, 0.f, 0.f, 0.f};
.LBB0_673:
	s_add_u32 s65, s26, 0x100
	v_mov_b64_e32 v[2:3], 0
	s_addc_u32 s66, s27, 0
	s_mov_b32 s67, -2
	v_mov_b64_e32 v[4:5], v[2:3]
	v_mov_b64_e32 v[18:19], v[2:3]
	v_mov_b64_e32 v[20:21], v[2:3]
	v_mov_b64_e32 v[6:7], v[2:3]
	v_mov_b64_e32 v[8:9], v[2:3]
	v_mov_b64_e32 v[22:23], v[2:3]
	v_mov_b64_e32 v[24:25], v[2:3]
	v_mov_b64_e32 v[10:11], v[2:3]
	v_mov_b64_e32 v[12:13], v[2:3]
	v_mov_b64_e32 v[26:27], v[2:3]
	v_mov_b64_e32 v[28:29], v[2:3]
	v_mov_b64_e32 v[14:15], v[2:3]
	v_mov_b64_e32 v[16:17], v[2:3]
	v_mov_b64_e32 v[30:31], v[2:3]
	v_mov_b64_e32 v[32:33], v[2:3]
	v_mov_b64_e32 v[34:35], v[2:3]
	v_mov_b64_e32 v[36:37], v[2:3]
	v_mov_b64_e32 v[50:51], v[2:3]
	v_mov_b64_e32 v[52:53], v[2:3]
	v_mov_b64_e32 v[38:39], v[2:3]
	v_mov_b64_e32 v[40:41], v[2:3]
	v_mov_b64_e32 v[54:55], v[2:3]
	v_mov_b64_e32 v[56:57], v[2:3]
	v_mov_b64_e32 v[42:43], v[2:3]
	v_mov_b64_e32 v[44:45], v[2:3]
	v_mov_b64_e32 v[58:59], v[2:3]
	v_mov_b64_e32 v[60:61], v[2:3]
	v_mov_b64_e32 v[46:47], v[2:3]
	v_mov_b64_e32 v[48:49], v[2:3]
	v_mov_b64_e32 v[62:63], v[2:3]
	v_mov_b64_e32 v[64:65], v[2:3]
	v_mov_b64_e32 v[66:67], v[2:3]
	v_mov_b64_e32 v[68:69], v[2:3]
	v_mov_b64_e32 v[82:83], v[2:3]
	v_mov_b64_e32 v[84:85], v[2:3]
	v_mov_b64_e32 v[70:71], v[2:3]
	v_mov_b64_e32 v[72:73], v[2:3]
	v_mov_b64_e32 v[86:87], v[2:3]
	v_mov_b64_e32 v[88:89], v[2:3]
	v_mov_b64_e32 v[74:75], v[2:3]
	v_mov_b64_e32 v[76:77], v[2:3]
	v_mov_b64_e32 v[90:91], v[2:3]
	v_mov_b64_e32 v[92:93], v[2:3]
	v_mov_b64_e32 v[78:79], v[2:3]
	v_mov_b64_e32 v[80:81], v[2:3]
	v_mov_b64_e32 v[94:95], v[2:3]
	v_mov_b64_e32 v[96:97], v[2:3]
	v_mov_b64_e32 v[98:99], v[2:3]
	v_mov_b64_e32 v[100:101], v[2:3]
	v_mov_b64_e32 v[114:115], v[2:3]
	v_mov_b64_e32 v[116:117], v[2:3]
	v_mov_b64_e32 v[102:103], v[2:3]
	v_mov_b64_e32 v[104:105], v[2:3]
	v_mov_b64_e32 v[118:119], v[2:3]
	v_mov_b64_e32 v[120:121], v[2:3]
	v_mov_b64_e32 v[106:107], v[2:3]
	v_mov_b64_e32 v[108:109], v[2:3]
	v_mov_b64_e32 v[122:123], v[2:3]
	v_mov_b64_e32 v[124:125], v[2:3]
	v_mov_b64_e32 v[110:111], v[2:3]
	v_mov_b64_e32 v[112:113], v[2:3]
	v_mov_b64_e32 v[126:127], v[2:3]
	v_mov_b64_e32 v[128:129], v[2:3]
